# attA: cold blocks (causal mask, rescale, no-DMA QK copy, first-pair wait) moved out of line so the steady-state path falls through
# baseline (speedup 1.0000x reference)
; __device__ __forceinline__ void unit(LAS unsigned char* lds, bf16_t* P1, const bf16_t* vaT, int b, int h, int qblk, float lam, const float* subln_w, const float* khalf) {
;     ...
;         if (jj + 2 < NT) asm volatile("s_waitcnt vmcnt(8) lgkmcnt(0)\n\ts_barrier" ::: "memory"); else if (jj + 1 < NT) asm volatile("s_waitcnt vmcnt(4) lgkmcnt(0)\n\ts_barrier" ::: "memory"); else asm volatile("s_waitcnt vmcnt(0) lgkmcnt(0)\n\ts_barrier" ::: "memory");
.La_flag_done2:
	s_cmp_eq_u32 s81, 0
	s_cbranch_scc1 .La_first

; __device__ __forceinline__ void unit(LAS unsigned char* lds, bf16_t* P1, const bf16_t* vaT, int b, int h, int qblk, float lam, const float* subln_w, const float* khalf) {
;     ...
;         { typedef int i32x4 __attribute__((ext_vector_type(4)));
;           const i32x4 fa = *(const LAS i32x4*)(lds + 4 * STG + (jj & 1) * 32), fb = *(const LAS i32x4*)(lds + 4 * STG + (jj & 1) * 32 + 16);
;           if (((fa[0] + fa[1]) + (fa[2] + fa[3])) + ((fb[0] + fb[1]) + (fb[2] + fb[3])) == 8) break; }
;         if (jj + 3 < NT) { DMA_TILE(j - 3, (stg + 3) & 3); }
;         const LAS unsigned char* kb = lds + stg * STG;
;         stg = (stg + 1) & 3;
;         f32x16 S0, S1;
;         { float slv = sl2; asm volatile("" : "+v"(slv));
; #pragma unroll
;           for (int r = 0; r < 16; ++r) { S0[r] = __builtin_fmaf(slv, (float)((r & 3) + 8 * (r >> 2)), sl2h); S1[r] = S0[r]; } }
; #pragma unroll
;         for (int ks = 0; ks < 4; ++ks) {
;             const bf16x8 a0 = *(const LAS bf16x8*)(kb + koff[ks]);
;             const bf16x8 a1 = *(const LAS bf16x8*)(kb + koff[ks] + 32 * 256);
;             S0 = MFMA32(a0, qf[ks], S0); S1 = MFMA32(a1, qf[ks], S1);
;         }
;         const int kv0 = 64 * j;
;         if (j >= NT - 2) {
; #pragma unroll
;             for (int r = 0; r < 16; ++r) { const int kv = kv0 + crow(r, hi); if (kv > qrow) S0[r] = -INFINITY; if (kv + 32 > qrow) S1[r] = -INFINITY; }
;         }
;         const float tb0 = sl2 * (float)(kv0 - qrow), tb1 = tb0 + sl2 * 32.f;
;         float mx0 = S0[0], mx1 = S1[0];
; #pragma unroll
;         for (int r = 1; r < 16; ++r) { mx0 = fmaxf(mx0, S0[r]); mx1 = fmaxf(mx1, S1[r]); }
;         float mt = fmaxf(mx0 + tb0, mx1 + tb1); mt = fmaxf(mt, __shfl_xor(mt, 32));
;         const bool skip = __all((mt < m - 24.f) || (mt == -INFINITY));
;         if (!skip) {
;         const float mn = fmaxf(m, mt); const float alpha = ex2(m - mn); m = mn;
;         const float c0 = tb0 - mn, c1 = tb1 - mn;
;         f32x2 ps2 = (f32x2){0.f, 0.f};
; #pragma unroll
;         for (int r = 0; r < 16; r += 2) { f32x2 a = (f32x2){S0[r], S0[r + 1]} + c0, bq = (f32x2){S1[r], S1[r + 1]} + c1;
;             a.x = ex2(a.x); a.y = ex2(a.y); bq.x = ex2(bq.x); bq.y = ex2(bq.y); S0[r] = a.x; S0[r + 1] = a.y; S1[r] = bq.x; S1[r + 1] = bq.y; ps2 = ps2 + a; ps2 = ps2 + bq; }
;         l = l * alpha + (ps2.x + ps2.y);
;         if (__any(alpha != 1.f)) {
.La_after_bar:
	s_lshl_b32 s82, s80, 15
	s_add_i32 s83, s82, 0x8000
	s_sub_i32 s100, s76, 64
	s_and_b32 s2, s81, 2
	s_lshl_b32 s2, s2, 4
	s_add_i32 s2, s2, 0x20000
	v_mov_b32_e32 v70, s2
	ds_read_b128 v[66:69], v70
	ds_read_b128 v[70:73], v70 offset:16
.La_noflagrd:
	v_add3_u32 v120, s82, v129, v151
	v_add3_u32 v201, s82, v185, v151
	ds_read_b128 v[192:195], v120
	ds_read_b128 v[196:199], v120 offset:8192
	v_add3_u32 v120, s82, v186, v151
	ds_read_b128 v[202:205], v201
	ds_read_b128 v[206:209], v201 offset:8192
	v_add3_u32 v201, s82, v187, v151
	ds_read_b128 v[210:213], v120
	ds_read_b128 v[214:217], v120 offset:8192
	ds_read_b128 v[218:221], v201
	ds_read_b128 v[222:225], v201 offset:8192
	s_waitcnt lgkmcnt(8)
	v_add3_u32 v66, v66, v67, v68
	v_add3_u32 v69, v69, v70, v71
	v_add_u32_e32 v72, v72, v73
	v_add3_u32 v66, v66, v69, v72
	v_cmp_eq_u32_e32 vcc, 8, v66
	s_cbranch_vccnz .LBB0_420
.La_nochk:
	s_cmp_lt_u32 s81, 2
	s_cbranch_scc1 .La_qk_nodmaA
	s_add_i32 s5, s81, 2
	s_cmp_ge_u32 s5, s73
	s_cbranch_scc1 .La_qk_nodmaA
	s_add_i32 s5, s82, 0x10000
	s_and_b32 s5, s5, 0x18000
	s_add_i32 s5, s72, s5
	s_mov_b32 m0, s5
	s_waitcnt lgkmcnt(4)
	v_mfma_f32_32x32x16_bf16 v[82:97], v[192:195], v[98:101], v[226:241]
	global_load_lds_dwordx4 v[140:141], off
	s_add_i32 m0, s5, 0x400
	v_mfma_f32_32x32x16_bf16 v[66:81], v[196:199], v[98:101], v[226:241]
	global_load_lds_dwordx4 v[138:139], off
	s_add_i32 m0, s5, 0x4000
	v_mfma_f32_32x32x16_bf16 v[82:97], v[202:205], v[102:105], v[82:97]
	global_load_lds_dwordx4 v134, s[44:45]
	s_add_i32 m0, s5, 0x4400
	v_mfma_f32_32x32x16_bf16 v[66:81], v[206:209], v[102:105], v[66:81]
	global_load_lds_dwordx4 v136, s[44:45]
	s_waitcnt lgkmcnt(0)
	v_mfma_f32_32x32x16_bf16 v[82:97], v[210:213], v[106:109], v[82:97]
	v_mfma_f32_32x32x16_bf16 v[66:81], v[214:217], v[106:109], v[66:81]
	v_mfma_f32_32x32x16_bf16 v[82:97], v[218:221], v[110:113], v[82:97]
	v_mfma_f32_32x32x16_bf16 v[66:81], v[222:225], v[110:113], v[66:81]
	s_add_u32 s44, s44, 0xffffff80
	s_addc_u32 s45, s45, -1
	v_lshl_add_u64 v[138:139], v[138:139], 0, s[38:39]
	v_lshl_add_u64 v[140:141], v[140:141], 0, s[38:39]
.La_qk_doneA:
	v_add_u32_e32 v244, s82, v168
	v_add_u32_e32 v245, s82, v169
	v_add_u32_e32 v246, s82, v170
	v_add_u32_e32 v247, s82, v171
	ds_read_b128 v[192:195], v244 offset:16384
	ds_read_b128 v[196:199], v244 offset:20480
	ds_read_b128 v[202:205], v244 offset:24576
	ds_read_b128 v[206:209], v244 offset:28672
	ds_read_b128 v[210:213], v245 offset:16384
	ds_read_b128 v[214:217], v245 offset:20480
	ds_read_b128 v[218:221], v245 offset:24576
	ds_read_b128 v[222:225], v245 offset:28672
	s_cmp_eq_u32 s81, 0
	s_cbranch_scc1 .La_maskA
.La_nomaskA:
	v_add_u32_e32 v0, s76, v190
	v_add_u32_e32 v0, 64, v0
	v_cvt_f32_i32_e32 v142, v0
	v_add_f32_e32 v143, v133, v121
	v_max3_f32 v0, v82, v83, v84
	v_max3_f32 v120, v66, v67, v68
	v_max3_f32 v0, v0, v85, v86
	v_max3_f32 v120, v120, v69, v70
	v_max3_f32 v0, v0, v87, v88
	v_max3_f32 v120, v120, v71, v72
	v_max3_f32 v0, v0, v89, v90
	v_max3_f32 v120, v120, v73, v74
	v_max3_f32 v0, v0, v91, v92
	v_max3_f32 v120, v120, v75, v76
	v_max3_f32 v0, v0, v93, v94
	v_max3_f32 v120, v120, v77, v78
	v_max3_f32 v0, v0, v95, v96
	v_max3_f32 v120, v120, v79, v80
	v_max_f32_e32 v0, v0, v97
	v_max_f32_e32 v120, v120, v81
	v_fma_f32 v248, v127, v142, v188
	v_fmac_f32_e32 v0, v127, v142
	v_add_f32_e32 v120, v248, v120
	v_max_f32_e32 v0, v0, v120
	v_mov_b32_e32 v120, v0
	s_nop 1
	v_permlane32_swap_b32_e32 v0, v120
	v_max_f32_e32 v0, v0, v120
	v_cmp_lt_f32_e32 vcc, v0, v143
	v_cmp_eq_f32_e64 s[4:5], v0, v184
	s_or_b64 s[4:5], vcc, s[4:5]
	s_cmp_eq_u64 s[4:5], exec
	s_cbranch_scc1 .La_endA
	v_max_f32_e32 v120, v133, v0
	v_mul_f32_e32 v142, v127, v142
	v_sub_f32_e32 v0, v133, v120
	v_exp_f32_e32 v0, v0
	v_sub_f32_e32 v142, v142, v120
	v_sub_f32_e32 v248, v248, v120
	v_mov_b32_e32 v133, v120
	v_cmp_neq_f32_e32 vcc, 1.0, v0
	s_cbranch_vccnz .La_rescaleA

; __device__ __forceinline__ int crow(int r, int hi) { return (r & 3) + 8 * (r >> 2) + 4 * hi; }
; __device__ __forceinline__ float ex2(float v) { return __builtin_amdgcn_exp2f(v); }
; __device__ __forceinline__ void unit(LAS unsigned char* lds, bf16_t* P1, const bf16_t* vaT, int b, int h, int qblk, float lam, const float* subln_w, const float* khalf) {
;     ...
;         if (j >= NT - 2) {
; #pragma unroll
;             for (int r = 0; r < 16; ++r) { const int kv = kv0 + crow(r, hi); if (kv > qrow) S0[r] = -INFINITY; if (kv + 32 > qrow) S1[r] = -INFINITY; }
;         }
;         const float tb0 = sl2 * (float)(kv0 - qrow), tb1 = tb0 + sl2 * 32.f;
;         float mx0 = S0[0], mx1 = S1[0];
; #pragma unroll
;         for (int r = 1; r < 16; ++r) { mx0 = fmaxf(mx0, S0[r]); mx1 = fmaxf(mx1, S1[r]); }
;         float mt = fmaxf(mx0 + tb0, mx1 + tb1); mt = fmaxf(mt, __shfl_xor(mt, 32));
;         const bool skip = __all((mt < m - 24.f) || (mt == -INFINITY));
;         if (!skip) {
;         const float mn = fmaxf(m, mt); const float alpha = ex2(m - mn); m = mn;
;         const float c0 = tb0 - mn, c1 = tb1 - mn;
;         f32x2 ps2 = (f32x2){0.f, 0.f};
; #pragma unroll
;         for (int r = 0; r < 16; r += 2) { f32x2 a = (f32x2){S0[r], S0[r + 1]} + c0, bq = (f32x2){S1[r], S1[r + 1]} + c1;
;             a.x = ex2(a.x); a.y = ex2(a.y); bq.x = ex2(bq.x); bq.y = ex2(bq.y); S0[r] = a.x; S0[r + 1] = a.y; S1[r] = bq.x; S1[r + 1] = bq.y; ps2 = ps2 + a; ps2 = ps2 + bq; }
;         l = l * alpha + (ps2.x + ps2.y);
;         if (__any(alpha != 1.f)) {
.La_qk_doneB:
	v_add_u32_e32 v244, s83, v168
	v_add_u32_e32 v245, s83, v169
	v_add_u32_e32 v246, s83, v170
	v_add_u32_e32 v247, s83, v171
	ds_read_b128 v[192:195], v244 offset:16384
	ds_read_b128 v[196:199], v244 offset:20480
	ds_read_b128 v[202:205], v244 offset:24576
	ds_read_b128 v[206:209], v244 offset:28672
	ds_read_b128 v[210:213], v245 offset:16384
	ds_read_b128 v[214:217], v245 offset:20480
	ds_read_b128 v[218:221], v245 offset:24576
	ds_read_b128 v[222:225], v245 offset:28672
	s_cmp_eq_u32 s81, 0
	s_cbranch_scc1 .La_maskB
.La_nomaskB:
	v_add_u32_e32 v0, s100, v190
	v_add_u32_e32 v0, 64, v0
	v_cvt_f32_i32_e32 v142, v0
	v_add_f32_e32 v143, v133, v121
	v_max3_f32 v0, v82, v83, v84
	v_max3_f32 v120, v66, v67, v68
	v_max3_f32 v0, v0, v85, v86
	v_max3_f32 v120, v120, v69, v70
	v_max3_f32 v0, v0, v87, v88
	v_max3_f32 v120, v120, v71, v72
	v_max3_f32 v0, v0, v89, v90
	v_max3_f32 v120, v120, v73, v74
	v_max3_f32 v0, v0, v91, v92
	v_max3_f32 v120, v120, v75, v76
	v_max3_f32 v0, v0, v93, v94
	v_max3_f32 v120, v120, v77, v78
	v_max3_f32 v0, v0, v95, v96
	v_max3_f32 v120, v120, v79, v80
	v_max_f32_e32 v0, v0, v97
	v_max_f32_e32 v120, v120, v81
	v_fma_f32 v248, v127, v142, v188
	v_fmac_f32_e32 v0, v127, v142
	v_add_f32_e32 v120, v248, v120
	v_max_f32_e32 v0, v0, v120
	v_mov_b32_e32 v120, v0
	s_nop 1
	v_permlane32_swap_b32_e32 v0, v120
	v_max_f32_e32 v0, v0, v120
	v_cmp_lt_f32_e32 vcc, v0, v143
	v_cmp_eq_f32_e64 s[4:5], v0, v184
	s_or_b64 s[4:5], vcc, s[4:5]
	s_cmp_eq_u64 s[4:5], exec
	s_cbranch_scc1 .La_endB
	v_max_f32_e32 v120, v133, v0
	v_mul_f32_e32 v142, v127, v142
	v_sub_f32_e32 v0, v133, v120
	v_exp_f32_e32 v0, v0
	v_sub_f32_e32 v142, v142, v120
	v_sub_f32_e32 v248, v248, v120
	v_mov_b32_e32 v133, v120
	v_cmp_neq_f32_e32 vcc, 1.0, v0
	s_cbranch_vccnz .La_rescaleB

; #define LAS __attribute__((address_space(3)))
; __device__ __forceinline__ void unit(LAS unsigned char* lds, bf16_t* P1, const bf16_t* vaT, int b, int h, int qblk, float lam, const float* subln_w, const float* khalf) {
;     ...
;         if (jj + 2 < NT) asm volatile("s_waitcnt vmcnt(8) lgkmcnt(0)\n\ts_barrier" ::: "memory"); else if (jj + 1 < NT) asm volatile("s_waitcnt vmcnt(4) lgkmcnt(0)\n\ts_barrier" ::: "memory"); else asm volatile("s_waitcnt vmcnt(0) lgkmcnt(0)\n\ts_barrier" ::: "memory");
;         { typedef int i32x4 __attribute__((ext_vector_type(4)));
;           const i32x4 fa = *(const LAS i32x4*)(lds + 4 * STG + (jj & 1) * 32), fb = *(const LAS i32x4*)(lds + 4 * STG + (jj & 1) * 32 + 16);
;           if (((fa[0] + fa[1]) + (fa[2] + fa[3])) + ((fb[0] + fb[1]) + (fb[2] + fb[3])) == 8) break; }
;         if (jj + 3 < NT) { DMA_TILE(j - 3, (stg + 3) & 3); }
;         const LAS unsigned char* kb = lds + stg * STG;
;         stg = (stg + 1) & 3;
;         f32x16 S0, S1;
;         { float slv = sl2; asm volatile("" : "+v"(slv));
; #pragma unroll
;           for (int r = 0; r < 16; ++r) { S0[r] = __builtin_fmaf(slv, (float)((r & 3) + 8 * (r >> 2)), sl2h); S1[r] = S0[r]; } }
; #pragma unroll
;         for (int ks = 0; ks < 4; ++ks) {
;             const bf16x8 a0 = *(const LAS bf16x8*)(kb + koff[ks]);
;             const bf16x8 a1 = *(const LAS bf16x8*)(kb + koff[ks] + 32 * 256);
;             S0 = MFMA32(a0, qf[ks], S0); S1 = MFMA32(a1, qf[ks], S1);
;         }
;         const int kv0 = 64 * j;
;         if (j >= NT - 2) {
; #pragma unroll
;             for (int r = 0; r < 16; ++r) { const int kv = kv0 + crow(r, hi); if (kv > qrow) S0[r] = -INFINITY; if (kv + 32 > qrow) S1[r] = -INFINITY; }
;         }
;         const float tb0 = sl2 * (float)(kv0 - qrow), tb1 = tb0 + sl2 * 32.f;
;         float mx0 = S0[0], mx1 = S1[0];
; #pragma unroll
;         for (int r = 1; r < 16; ++r) { mx0 = fmaxf(mx0, S0[r]); mx1 = fmaxf(mx1, S1[r]); }
;         float mt = fmaxf(mx0 + tb0, mx1 + tb1); mt = fmaxf(mt, __shfl_xor(mt, 32));
;         const bool skip = __all((mt < m - 24.f) || (mt == -INFINITY));
;         if (!skip) {
;         const float mn = fmaxf(m, mt); const float alpha = ex2(m - mn); m = mn;
;         const float c0 = tb0 - mn, c1 = tb1 - mn;
;         f32x2 ps2 = (f32x2){0.f, 0.f};
; #pragma unroll
.La_endB:
	s_add_i32 s80, s80, 2
	s_and_b32 s80, s80, 3
	s_add_i32 s4, s59, s76
	s_add_i32 s81, s81, 2
	s_sub_i32 s76, s76, 0x80
	s_cmp_eq_u32 s4, 0
	s_cbranch_scc0 .La_top
	s_branch .LBB0_420
.La_first:
	s_cmp_gt_u32 s73, 2
	s_cbranch_scc0 .La_w0
	s_waitcnt vmcnt(4) lgkmcnt(0)
	s_barrier
	s_branch .La_after_bar
.La_qk_nodmaA:
	s_waitcnt lgkmcnt(4)
	v_mfma_f32_32x32x16_bf16 v[82:97], v[192:195], v[98:101], v[226:241]
	v_mfma_f32_32x32x16_bf16 v[66:81], v[196:199], v[98:101], v[226:241]
	v_mfma_f32_32x32x16_bf16 v[82:97], v[202:205], v[102:105], v[82:97]
	v_mfma_f32_32x32x16_bf16 v[66:81], v[206:209], v[102:105], v[66:81]
	s_waitcnt lgkmcnt(0)
	v_mfma_f32_32x32x16_bf16 v[82:97], v[210:213], v[106:109], v[82:97]
	v_mfma_f32_32x32x16_bf16 v[66:81], v[214:217], v[106:109], v[66:81]
	v_mfma_f32_32x32x16_bf16 v[82:97], v[218:221], v[110:113], v[82:97]
	v_mfma_f32_32x32x16_bf16 v[66:81], v[222:225], v[110:113], v[66:81]
	s_branch .La_qk_doneA
.La_maskA:
	v_add_u32_e32 v243, s76, v189
	v_add_u32_e32 v250, 0x60, v243
	v_add_u32_e32 v251, 64, v243
	v_cmp_le_i32_e32 vcc, v250, v125
	s_nop 6
	v_cndmask_b32_e32 v66, v184, v66, vcc
	v_cmp_lt_i32_e32 vcc, v251, v125
	s_nop 1
	v_cndmask_b32_e32 v83, v184, v83, vcc
	v_cmp_le_i32_e32 vcc, v251, v125
	v_add_u32_e32 v251, 0x61, v243
	s_nop 0
	v_cndmask_b32_e32 v82, v184, v82, vcc
	v_cmp_le_i32_e32 vcc, v251, v125
	v_add_u32_e32 v251, 0x42, v243
	s_nop 0
	v_cndmask_b32_e32 v67, v184, v67, vcc
	v_cmp_le_i32_e32 vcc, v251, v125
	v_add_u32_e32 v251, 0x62, v243
	s_nop 0
	v_cndmask_b32_e32 v84, v184, v84, vcc
	v_cmp_le_i32_e32 vcc, v251, v125
	v_add_u32_e32 v251, 0x43, v243
	s_nop 0
	v_cndmask_b32_e32 v68, v184, v68, vcc
	v_cmp_le_i32_e32 vcc, v251, v125
	v_add_u32_e32 v251, 0x63, v243
	s_nop 0
	v_cndmask_b32_e32 v85, v184, v85, vcc
	v_cmp_le_i32_e32 vcc, v251, v125
	v_add_u32_e32 v251, 0x48, v243
	s_nop 0
	v_cndmask_b32_e32 v69, v184, v69, vcc
	v_cmp_le_i32_e32 vcc, v251, v125
	v_add_u32_e32 v251, 0x68, v243
	s_nop 0
	v_cndmask_b32_e32 v86, v184, v86, vcc
	v_cmp_le_i32_e32 vcc, v251, v125
	v_add_u32_e32 v251, 0x49, v243
	s_nop 0
	v_cndmask_b32_e32 v70, v184, v70, vcc
	v_cmp_le_i32_e32 vcc, v251, v125
	v_add_u32_e32 v251, 0x69, v243
	s_nop 0
	v_cndmask_b32_e32 v87, v184, v87, vcc
	v_cmp_le_i32_e32 vcc, v251, v125
	v_add_u32_e32 v251, 0x4a, v243
	s_nop 0
	v_cndmask_b32_e32 v71, v184, v71, vcc
	v_cmp_le_i32_e32 vcc, v251, v125
	v_add_u32_e32 v251, 0x6a, v243
	s_nop 0
	v_cndmask_b32_e32 v88, v184, v88, vcc
	v_cmp_le_i32_e32 vcc, v251, v125
	v_add_u32_e32 v251, 0x4b, v243
	s_nop 0
	v_cndmask_b32_e32 v72, v184, v72, vcc
	v_cmp_le_i32_e32 vcc, v251, v125
	v_add_u32_e32 v251, 0x6b, v243
	s_nop 0
	v_cndmask_b32_e32 v89, v184, v89, vcc
	v_cmp_le_i32_e32 vcc, v251, v125
	v_add_u32_e32 v251, 0x50, v243
	s_nop 0
	v_cndmask_b32_e32 v73, v184, v73, vcc
	v_cmp_le_i32_e32 vcc, v251, v125
	v_add_u32_e32 v251, 0x70, v243
	s_nop 0
	v_cndmask_b32_e32 v90, v184, v90, vcc
	v_cmp_le_i32_e32 vcc, v251, v125
	v_add_u32_e32 v251, 0x51, v243
	s_nop 0
	v_cndmask_b32_e32 v74, v184, v74, vcc
	v_cmp_le_i32_e32 vcc, v251, v125
	v_add_u32_e32 v251, 0x71, v243
	s_nop 0
	v_cndmask_b32_e32 v91, v184, v91, vcc
	v_cmp_le_i32_e32 vcc, v251, v125
	v_add_u32_e32 v251, 0x52, v243
	s_nop 0
	v_cndmask_b32_e32 v75, v184, v75, vcc
	v_cmp_le_i32_e32 vcc, v251, v125
	v_add_u32_e32 v251, 0x72, v243
	s_nop 0
	v_cndmask_b32_e32 v92, v184, v92, vcc
	v_cmp_le_i32_e32 vcc, v251, v125
	v_add_u32_e32 v251, 0x53, v243
	s_nop 0
	v_cndmask_b32_e32 v76, v184, v76, vcc
	v_cmp_le_i32_e32 vcc, v251, v125
	v_add_u32_e32 v251, 0x73, v243
	s_nop 0
	v_cndmask_b32_e32 v93, v184, v93, vcc
	v_cmp_le_i32_e32 vcc, v251, v125
	v_add_u32_e32 v251, 0x58, v243
	s_nop 0
	v_cndmask_b32_e32 v77, v184, v77, vcc
	v_cmp_le_i32_e32 vcc, v251, v125
	v_add_u32_e32 v251, 0x78, v243
	s_nop 0
	v_cndmask_b32_e32 v94, v184, v94, vcc
	v_cmp_le_i32_e32 vcc, v251, v125
	v_add_u32_e32 v251, 0x59, v243
	s_nop 0
	v_cndmask_b32_e32 v78, v184, v78, vcc
	v_cmp_le_i32_e32 vcc, v251, v125
	v_add_u32_e32 v251, 0x79, v243
	s_nop 0
	v_cndmask_b32_e32 v95, v184, v95, vcc
	v_cmp_le_i32_e32 vcc, v251, v125
	v_add_u32_e32 v251, 0x5a, v243
	s_nop 0
	v_cndmask_b32_e32 v79, v184, v79, vcc
	v_cmp_le_i32_e32 vcc, v251, v125
	v_add_u32_e32 v251, 0x7a, v243
	s_nop 0
	v_cndmask_b32_e32 v96, v184, v96, vcc
	v_cmp_le_i32_e32 vcc, v251, v125
	v_add_u32_e32 v251, 0x5b, v243
	v_add_u32_e32 v243, 0x7b, v243
	v_cndmask_b32_e32 v80, v184, v80, vcc
	v_cmp_le_i32_e32 vcc, v251, v125
	s_nop 1
	v_cndmask_b32_e32 v97, v184, v97, vcc
	v_cmp_le_i32_e32 vcc, v243, v125
	s_nop 1
	v_cndmask_b32_e32 v81, v184, v81, vcc
	s_branch .La_nomaskA
.La_rescaleA:
	v_pk_mul_f32 v[64:65], v[64:65], v[0:1] op_sel_hi:[1,0]
	v_pk_mul_f32 v[62:63], v[62:63], v[0:1] op_sel_hi:[1,0]
	v_pk_mul_f32 v[60:61], v[60:61], v[0:1] op_sel_hi:[1,0]
	v_pk_mul_f32 v[58:59], v[58:59], v[0:1] op_sel_hi:[1,0]
	v_pk_mul_f32 v[56:57], v[56:57], v[0:1] op_sel_hi:[1,0]
	v_pk_mul_f32 v[54:55], v[54:55], v[0:1] op_sel_hi:[1,0]
	v_pk_mul_f32 v[52:53], v[52:53], v[0:1] op_sel_hi:[1,0]
	v_pk_mul_f32 v[50:51], v[50:51], v[0:1] op_sel_hi:[1,0]
	v_pk_mul_f32 v[48:49], v[48:49], v[0:1] op_sel_hi:[1,0]
	v_pk_mul_f32 v[46:47], v[46:47], v[0:1] op_sel_hi:[1,0]
	v_pk_mul_f32 v[44:45], v[44:45], v[0:1] op_sel_hi:[1,0]
	v_pk_mul_f32 v[42:43], v[42:43], v[0:1] op_sel_hi:[1,0]
	v_pk_mul_f32 v[40:41], v[40:41], v[0:1] op_sel_hi:[1,0]
	v_pk_mul_f32 v[38:39], v[38:39], v[0:1] op_sel_hi:[1,0]
	v_pk_mul_f32 v[36:37], v[36:37], v[0:1] op_sel_hi:[1,0]
	v_pk_mul_f32 v[34:35], v[34:35], v[0:1] op_sel_hi:[1,0]
	v_pk_mul_f32 v[32:33], v[32:33], v[0:1] op_sel_hi:[1,0]
	v_pk_mul_f32 v[30:31], v[30:31], v[0:1] op_sel_hi:[1,0]
	v_pk_mul_f32 v[28:29], v[28:29], v[0:1] op_sel_hi:[1,0]
	v_pk_mul_f32 v[26:27], v[26:27], v[0:1] op_sel_hi:[1,0]
	v_pk_mul_f32 v[24:25], v[24:25], v[0:1] op_sel_hi:[1,0]
	v_pk_mul_f32 v[22:23], v[22:23], v[0:1] op_sel_hi:[1,0]
	v_pk_mul_f32 v[20:21], v[20:21], v[0:1] op_sel_hi:[1,0]
	v_pk_mul_f32 v[18:19], v[18:19], v[0:1] op_sel_hi:[1,0]
	v_pk_mul_f32 v[16:17], v[16:17], v[0:1] op_sel_hi:[1,0]
	v_pk_mul_f32 v[14:15], v[14:15], v[0:1] op_sel_hi:[1,0]
	v_pk_mul_f32 v[12:13], v[12:13], v[0:1] op_sel_hi:[1,0]
	v_pk_mul_f32 v[10:11], v[10:11], v[0:1] op_sel_hi:[1,0]
	v_pk_mul_f32 v[8:9], v[8:9], v[0:1] op_sel_hi:[1,0]
	v_pk_mul_f32 v[6:7], v[6:7], v[0:1] op_sel_hi:[1,0]
	v_pk_mul_f32 v[4:5], v[4:5], v[0:1] op_sel_hi:[1,0]
	v_pk_mul_f32 v[2:3], v[2:3], v[0:1] op_sel_hi:[1,0]
	s_branch .La_norescaleA

; __device__ __forceinline__ int crow(int r, int hi) { return (r & 3) + 8 * (r >> 2) + 4 * hi; }
; __device__ __forceinline__ void unit(LAS unsigned char* lds, bf16_t* P1, const bf16_t* vaT, int b, int h, int qblk, float lam, const float* subln_w, const float* khalf) {
;     ...
;         if (j >= NT - 2) {
; #pragma unroll
;             for (int r = 0; r < 16; ++r) { const int kv = kv0 + crow(r, hi); if (kv > qrow) S0[r] = -INFINITY; if (kv + 32 > qrow) S1[r] = -INFINITY; }
;         }
.La_maskB:
	v_add_u32_e32 v243, s100, v189
	v_add_u32_e32 v250, 0x60, v243
	v_add_u32_e32 v251, 64, v243
	v_cmp_le_i32_e32 vcc, v250, v125
	s_nop 6
	v_cndmask_b32_e32 v66, v184, v66, vcc
	v_cmp_lt_i32_e32 vcc, v251, v125
	s_nop 1
	v_cndmask_b32_e32 v83, v184, v83, vcc
	v_cmp_le_i32_e32 vcc, v251, v125
	v_add_u32_e32 v251, 0x61, v243
	s_nop 0
	v_cndmask_b32_e32 v82, v184, v82, vcc
	v_cmp_le_i32_e32 vcc, v251, v125
	v_add_u32_e32 v251, 0x42, v243
	s_nop 0
	v_cndmask_b32_e32 v67, v184, v67, vcc
	v_cmp_le_i32_e32 vcc, v251, v125
	v_add_u32_e32 v251, 0x62, v243
	s_nop 0
	v_cndmask_b32_e32 v84, v184, v84, vcc
	v_cmp_le_i32_e32 vcc, v251, v125
	v_add_u32_e32 v251, 0x43, v243
	s_nop 0
	v_cndmask_b32_e32 v68, v184, v68, vcc
	v_cmp_le_i32_e32 vcc, v251, v125
	v_add_u32_e32 v251, 0x63, v243
	s_nop 0
	v_cndmask_b32_e32 v85, v184, v85, vcc
	v_cmp_le_i32_e32 vcc, v251, v125
	v_add_u32_e32 v251, 0x48, v243
	s_nop 0
	v_cndmask_b32_e32 v69, v184, v69, vcc
	v_cmp_le_i32_e32 vcc, v251, v125
	v_add_u32_e32 v251, 0x68, v243
	s_nop 0
	v_cndmask_b32_e32 v86, v184, v86, vcc
	v_cmp_le_i32_e32 vcc, v251, v125
	v_add_u32_e32 v251, 0x49, v243
	s_nop 0
	v_cndmask_b32_e32 v70, v184, v70, vcc
	v_cmp_le_i32_e32 vcc, v251, v125
	v_add_u32_e32 v251, 0x69, v243
	s_nop 0
	v_cndmask_b32_e32 v87, v184, v87, vcc
	v_cmp_le_i32_e32 vcc, v251, v125
	v_add_u32_e32 v251, 0x4a, v243
	s_nop 0
	v_cndmask_b32_e32 v71, v184, v71, vcc
	v_cmp_le_i32_e32 vcc, v251, v125
	v_add_u32_e32 v251, 0x6a, v243
	s_nop 0
	v_cndmask_b32_e32 v88, v184, v88, vcc
	v_cmp_le_i32_e32 vcc, v251, v125
	v_add_u32_e32 v251, 0x4b, v243
	s_nop 0
	v_cndmask_b32_e32 v72, v184, v72, vcc
	v_cmp_le_i32_e32 vcc, v251, v125
	v_add_u32_e32 v251, 0x6b, v243
	s_nop 0
	v_cndmask_b32_e32 v89, v184, v89, vcc
	v_cmp_le_i32_e32 vcc, v251, v125
	v_add_u32_e32 v251, 0x50, v243
	s_nop 0
	v_cndmask_b32_e32 v73, v184, v73, vcc
	v_cmp_le_i32_e32 vcc, v251, v125
	v_add_u32_e32 v251, 0x70, v243
	s_nop 0
	v_cndmask_b32_e32 v90, v184, v90, vcc
	v_cmp_le_i32_e32 vcc, v251, v125
	v_add_u32_e32 v251, 0x51, v243
	s_nop 0
	v_cndmask_b32_e32 v74, v184, v74, vcc
	v_cmp_le_i32_e32 vcc, v251, v125
	v_add_u32_e32 v251, 0x71, v243
	s_nop 0
	v_cndmask_b32_e32 v91, v184, v91, vcc
	v_cmp_le_i32_e32 vcc, v251, v125
	v_add_u32_e32 v251, 0x52, v243
	s_nop 0
	v_cndmask_b32_e32 v75, v184, v75, vcc
	v_cmp_le_i32_e32 vcc, v251, v125
	v_add_u32_e32 v251, 0x72, v243
	s_nop 0
	v_cndmask_b32_e32 v92, v184, v92, vcc
	v_cmp_le_i32_e32 vcc, v251, v125
	v_add_u32_e32 v251, 0x53, v243
	s_nop 0
	v_cndmask_b32_e32 v76, v184, v76, vcc
	v_cmp_le_i32_e32 vcc, v251, v125
	v_add_u32_e32 v251, 0x73, v243
	s_nop 0
	v_cndmask_b32_e32 v93, v184, v93, vcc
	v_cmp_le_i32_e32 vcc, v251, v125
	v_add_u32_e32 v251, 0x58, v243
	s_nop 0
	v_cndmask_b32_e32 v77, v184, v77, vcc
	v_cmp_le_i32_e32 vcc, v251, v125
	v_add_u32_e32 v251, 0x78, v243
	s_nop 0
	v_cndmask_b32_e32 v94, v184, v94, vcc
	v_cmp_le_i32_e32 vcc, v251, v125
	v_add_u32_e32 v251, 0x59, v243
	s_nop 0
	v_cndmask_b32_e32 v78, v184, v78, vcc
	v_cmp_le_i32_e32 vcc, v251, v125
	v_add_u32_e32 v251, 0x79, v243
	s_nop 0
	v_cndmask_b32_e32 v95, v184, v95, vcc
	v_cmp_le_i32_e32 vcc, v251, v125
	v_add_u32_e32 v251, 0x5a, v243
	s_nop 0
	v_cndmask_b32_e32 v79, v184, v79, vcc
	v_cmp_le_i32_e32 vcc, v251, v125
	v_add_u32_e32 v251, 0x7a, v243
	s_nop 0
	v_cndmask_b32_e32 v96, v184, v96, vcc
	v_cmp_le_i32_e32 vcc, v251, v125
	v_add_u32_e32 v251, 0x5b, v243
	v_add_u32_e32 v243, 0x7b, v243
	v_cndmask_b32_e32 v80, v184, v80, vcc
	v_cmp_le_i32_e32 vcc, v251, v125
	s_nop 1
	v_cndmask_b32_e32 v97, v184, v97, vcc
	v_cmp_le_i32_e32 vcc, v243, v125
	s_nop 1
	v_cndmask_b32_e32 v81, v184, v81, vcc
	s_branch .La_nomaskB
